# Q rows of attention / retention blocks (read once per block) loaded non-temporal
# baseline (speedup 1.0000x reference)
; __device__ __forceinline__ void attn_block(const bf16_t* __restrict__ proj, bf16_t* __restrict__ mixed, int b, int h, int qb, char* lds) {
;     int tid_ = threadIdx.x; asm volatile("" : "+v"(tid_));
;     const int tid = tid_, wid = __builtin_amdgcn_readfirstlane(tid >> 6), lane = tid & 63, r32 = lane & 31, hi = lane >> 5;
;     constexpr int SHM = 16384;
;     char* V_lds = lds; char* K_lds = lds + 2 * SHM;
;     float* wsf = (float*)(lds + 65536) + wid * 64; float* li_l = wsf; float* al_l = wsf + 32;
;     const bf16_t* Qp = proj + (size_t)(b * SEQ + qb * 256) * LDQ + h * 128;
;     const bf16_t* Kp = proj + (size_t)(b * SEQ) * LDQ + 1024 + h * 128;
;     const bf16_t* Vp = Kp + 1024;
;     bf16_t* Op = mixed + (size_t)(b * SEQ + qb * 256 + wid * 32) * LDO + h * 128;
;     const int NT = 4 * (qb + 1);
;     const int qlo = qb * 256 + wid * 32, qm = qlo + r32 - 4 * hi;
;     const float slr = __builtin_amdgcn_exp2f(-(float)(h + 1)) * (1.0f / SCALE);
;     bf16x8 qr[8];
; #pragma unroll
;     for (int d0 = 0; d0 < 8; ++d0) qr[d0] = *(const bf16x8*)(Qp + (size_t)(wid * 32 + r32) * LDQ + d0 * 16 + hi * 8);
;     const int lb = wid * 1024 + lane * 16;
;     const int krow = lb >> 8, kch = ((lb >> 4) & 15) ^ (krow & 7);
;     const bf16_t* kg = Kp + (size_t)krow * LDQ + kch * 8;
;     const int stv = lb >> 9, kkv = ((stv >> 2) << 3) | ((lb >> 6) & 7), kvv = (kkv & ~0xC) | ((kkv & 4) << 1) | ((kkv & 8) >> 1);
;     const bf16_t* vg = Vp + (size_t)kvv * LDQ + (stv & 3) * 32 + ((lb >> 4) & 3) * 8;
;     ...
;     FA_DMA(0, 0);
;     asm volatile("s_waitcnt vmcnt(0)" ::: "memory");
;     __syncthreads();
;     float m_reg = -1e30f, l_reg = 0.f; f32x16 o[4];
; #pragma unroll
;     for (int d = 0; d < 4; ++d)
; #pragma unroll
;         for (int r = 0; r < 16; ++r) o[d][r] = 0.f;
;     const int vb0 = (int)(uintptr_t)V_lds + v_rd_base(lane);
;     const int dq15 = qm & 15, dq3 = qm & 3, r0 = (dq15 & 3) + 4 * (dq15 >> 3);
;     const bool lane_valid = (dq15 & 4) == 0, r0odd = (r0 & 1) != 0;
;     const bool is1 = r0 == 1, is2 = r0 == 2, is3 = r0 == 3, is4 = r0 == 4, is5 = r0 == 5, is6 = r0 == 6, is7 = r0 == 7;
;     const bool rp0 = (r0 >> 1) == 0, rp1 = (r0 >> 1) == 1, rp2 = (r0 >> 1) == 2, rp3 = (r0 >> 1) == 3;
;     const float fc0 = slr * (float)((r0 & 3) + 8 * (r0 >> 2));
.LBB0_310:
	s_xor_b64 s[92:93], s[0:1], -1
	v_mov_b32_e32 v16, v185
	s_and_b64 s[0:1], s[0:1], exec
	s_cselect_b32 s56, s73, s72
	v_readfirstlane_b32 s4, v16
	s_and_b32 s0, s4, 0x3fffffc0
	s_lshl_b32 s0, s0, 2
	s_lshl_b32 s6, s56, 8
	s_add_i32 s0, s0, 0
	s_or_b32 s83, s6, s74
	s_ashr_i32 s5, s4, 6
	s_add_i32 s57, s0, 0x10000
	s_mul_i32 s0, s83, 0x3800
	s_mul_hi_i32 s1, s83, 0x3800
	s_add_u32 s0, s75, s0
	v_and_b32_e32 v210, 31, v16
	s_addc_u32 s1, s80, s1
	s_lshl_b32 s64, s5, 5
	v_bfe_u32 v209, v16, 5, 1
	v_or_b32_e32 v0, s64, v210
	v_mov_b64_e32 v[2:3], s[0:1]
	v_and_b32_e32 v17, 63, v16
	v_mad_i64_i32 v[2:3], s[0:1], v0, s55, v[2:3]
	v_lshlrev_b32_e32 v0, 4, v209
	s_add_i32 s65, s64, s6
	v_lshl_add_u64 v[2:3], v[2:3], 0, v[0:1]
	s_lshl_b32 s5, s5, 10
	v_lshlrev_b32_e32 v19, 4, v17
	v_lshlrev_b32_e32 v207, 2, v209
	global_load_dwordx4 v[144:147], v[2:3], off nt
	global_load_dwordx4 v[148:151], v[2:3], off offset:32 nt
	global_load_dwordx4 v[152:155], v[2:3], off offset:64 nt
	global_load_dwordx4 v[156:159], v[2:3], off offset:96 nt
	global_load_dwordx4 v[160:163], v[2:3], off offset:128 nt
	global_load_dwordx4 v[164:167], v[2:3], off offset:160 nt
	global_load_dwordx4 v[168:171], v[2:3], off offset:192 nt
	global_load_dwordx4 v[172:175], v[2:3], off offset:224 nt
	v_or_b32_e32 v2, s65, v210
	v_or_b32_e32 v12, s5, v19
	v_sub_u32_e32 v18, v2, v207
	v_ashrrev_i32_e32 v2, 8, v12
	v_and_b32_e32 v3, 15, v16
	v_bitop3_b32 v6, v2, v3, 7 bitop3:0x6c
	v_mul_hi_i32_i24_e32 v3, 0x3800, v2
	v_mul_i32_i24_e32 v2, 0x3800, v2
	s_ashr_i32 s0, s4, 4
	v_lshrrev_b32_e32 v10, 1, v16
	v_lshl_add_u64 v[4:5], s[70:71], 0, v[2:3]
	v_lshlrev_b32_e32 v6, 4, v6
	v_mov_b32_e32 v7, v1
	v_and_b32_e32 v10, 8, v10
	s_lshr_b32 s1, s0, 1
	v_lshl_add_u64 v[4:5], v[4:5], 0, v[6:7]
	v_bfe_u32 v7, v16, 2, 2
	s_and_b32 s94, s1, 4
	v_and_or_b32 v20, s0, -16, v10
	v_or3_b32 v10, v20, v7, s94
	v_lshrrev_b32_e32 v12, 3, v12
	v_mad_i64_i32 v[10:11], s[0:1], v10, s55, v[176:177]
	v_and_b32_e32 v12, 0xc0, v12
	v_mov_b32_e32 v13, v1
	v_lshl_add_u64 v[10:11], v[10:11], 0, v[12:13]
	v_lshlrev_b32_e32 v13, 3, v17
	v_and_b32_e32 v21, 24, v13
	v_lshlrev_b32_e32 v14, 1, v21
	v_mov_b32_e32 v15, v1
	s_add_i32 s87, s5, 0
	v_lshl_add_u64 v[8:9], v[4:5], 0, s[66:67]
	v_lshl_add_u64 v[10:11], v[10:11], 0, v[14:15]
	s_add_i32 m0, s87, 0x8000
	v_lshl_add_u64 v[14:15], v[10:11], 0, s[66:67]
	global_load_lds_dwordx4 v[8:9], off
	s_mov_b32 m0, s87
	v_lshl_add_u64 v[4:5], v[4:5], 0, s[68:69]
	global_load_lds_dwordx4 v[14:15], off
	s_add_i32 m0, s87, 0xa000
	s_lshl_b32 s88, s56, 2
	global_load_lds_dwordx4 v[4:5], off
	v_lshl_add_u64 v[4:5], v[10:11], 0, s[68:69]
	s_add_i32 m0, s87, 0x2000
	v_lshrrev_b32_e32 v11, 1, v18
	global_load_lds_dwordx4 v[4:5], off
	v_and_b32_e32 v10, 3, v16
	v_and_b32_e32 v11, 4, v11
	v_and_b32_e32 v8, 0x100, v13
	v_or_b32_e32 v13, v11, v10
	v_and_b32_e32 v14, 4, v18
	s_add_i32 s88, s88, 4
	v_cmp_eq_u32_e64 s[0:1], 0, v14
	v_cmp_eq_u32_e64 s[4:5], 1, v13
	v_cmp_eq_u32_e64 s[6:7], 2, v13
	v_cmp_eq_u32_e64 s[8:9], 3, v13
	v_cmp_eq_u32_e64 s[10:11], 4, v13
	v_cmp_eq_u32_e64 s[12:13], 5, v13
	v_cmp_eq_u32_e64 s[14:15], 6, v13
	v_cmp_eq_u32_e64 s[16:17], 7, v13
	v_lshrrev_b32_e32 v14, 1, v13
	v_cmp_gt_u32_e64 s[18:19], 2, v13
	s_or_b32 s78, s65, 31
	v_lshlrev_b32_e32 v13, 4, v16
	s_movk_i32 s26, 0x70
	v_and_b32_e32 v4, 0xc0, v19
	v_lshlrev_b32_e32 v5, 1, v16
	v_cmp_eq_u32_e64 s[20:21], 1, v14
	v_cmp_eq_u32_e64 s[22:23], 2, v14
	v_cmp_eq_u32_e64 s[24:25], 3, v14
	v_and_b32_e32 v14, 0x70, v13
	v_bitop3_b32 v214, v0, v13, s26 bitop3:0x78
	s_movk_i32 s26, 0x60
	s_cmp_lg_u32 0, -1
	v_and_b32_e32 v5, 32, v5
	v_bitop3_b32 v215, v0, v14, 32 bitop3:0x36
	v_bitop3_b32 v216, v0, v14, 64 bitop3:0x36
	v_bitop3_b32 v217, v0, v14, s26 bitop3:0x36
	v_lshl_add_u32 v225, v210, 2, s57
	v_add_u32_e32 v208, s57, v0
	v_or3_b32 v0, v4, v8, v21
	s_cselect_b32 s57, 0, 0
	v_and_b32_e32 v9, 15, v18
	v_cmp_eq_u32_e64 s[30:31], 1, v10
	v_cmp_eq_u32_e64 s[36:37], 2, v10
	v_add3_u32 v231, v5, s57, v0
	s_mul_i32 s56, s56, 0x380000
	v_or3_b32 v0, v20, s94, v7
	v_lshl_or_b32 v11, v11, 1, v10
	v_cmp_eq_u32_e64 s[26:27], 0, v10
	v_cndmask_b32_e64 v14, 0, v182, s[30:31]
	v_cmp_eq_u32_e64 s[34:35], 1, v9
	v_cndmask_b32_e64 v15, 0, v182, s[36:37]
	v_cmp_eq_u32_e64 s[38:39], 2, v9
	v_cmp_eq_u32_e64 s[40:41], 3, v10
	v_cmp_eq_u32_e64 s[46:47], 9, v9
	v_cmp_eq_u32_e64 s[48:49], 10, v9
	s_add_u32 s79, s56, 0x380000
	v_mad_i64_i32 v[4:5], s[56:57], v0, s55, 0
	v_lshlrev_b32_e32 v0, 4, v10
	s_waitcnt vmcnt(0)
; __device__ __forceinline__ int v_rd_base(int lane) { return ((lane & 3) << 3) | (((lane >> 2) & 3) << 6) | (((lane >> 4) & 1) << 5) | (((lane >> 5) & 1) << 8); }
; __device__ __forceinline__ void attn_block(const bf16_t* __restrict__ proj, bf16_t* __restrict__ mixed, int b, int h, int qb, char* lds) {
;     ...
;     asm volatile("s_waitcnt vmcnt(0)" ::: "memory");
;     __syncthreads();
;     float m_reg = -1e30f, l_reg = 0.f; f32x16 o[4];
; #pragma unroll
;     for (int d = 0; d < 4; ++d)
; #pragma unroll
;         for (int r = 0; r < 16; ++r) o[d][r] = 0.f;
;     const int vb0 = (int)(uintptr_t)V_lds + v_rd_base(lane);
;     const int dq15 = qm & 15, dq3 = qm & 3, r0 = (dq15 & 3) + 4 * (dq15 >> 3);
;     const bool lane_valid = (dq15 & 4) == 0, r0odd = (r0 & 1) != 0;
;     const bool is1 = r0 == 1, is2 = r0 == 2, is3 = r0 == 3, is4 = r0 == 4, is5 = r0 == 5, is6 = r0 == 6, is7 = r0 == 7;
;     const bool rp0 = (r0 >> 1) == 0, rp1 = (r0 >> 1) == 1, rp2 = (r0 >> 1) == 2, rp3 = (r0 >> 1) == 3;
;     const float fc0 = slr * (float)((r0 & 3) + 8 * (r0 >> 2));
;     for (int t = 0; t < NT; ++t) {
;         const int buf = t & 1, kb = t * 64;
;         if (t + 1 < NT) FA_DMA(kb + 64, buf ^ 1);
;         if (kb <= qlo + 31) {
	v_and_b32_e32 v211, 1, v16
	v_cvt_f32_ubyte0_e32 v11, v11
	v_cndmask_b32_e64 v13, 0, v182, s[26:27]
	v_cmp_eq_u32_e64 s[28:29], 0, v9
	v_cndmask_b32_e64 v219, v14, v183, s[34:35]
	v_cndmask_b32_e64 v220, v15, v183, s[38:39]
	v_cndmask_b32_e64 v16, 0, v182, s[40:41]
	v_cmp_eq_u32_e64 s[42:43], 3, v9
	v_cmp_eq_u32_e64 s[44:45], 8, v9
	v_cndmask_b32_e64 v223, v14, v183, s[46:47]
	v_cndmask_b32_e64 v224, v15, v183, s[48:49]
	v_cmp_eq_u32_e64 s[50:51], 11, v9
	v_or3_b32 v4, v4, v12, v0
	v_or_b32_e32 v2, v2, v6
	v_mov_b32_e32 v14, v1
	v_mov_b32_e32 v15, v1
	v_mul_f32_e32 v212, v203, v11
	v_cndmask_b32_e64 v218, v13, v183, s[28:29]
	v_cndmask_b32_e64 v221, v16, v183, s[42:43]
	v_cndmask_b32_e64 v222, v13, v183, s[44:45]
	v_cndmask_b32_e64 v226, v16, v183, s[50:51]
	v_fma_f32 v227, v203, v11, v204
	v_fma_f32 v228, v203, v11, v205
	v_fma_f32 v229, v203, v11, v206
	v_cmp_gt_u32_e64 s[52:53], 32, v17
	v_lshl_add_u64 v[178:179], s[90:91], 0, v[4:5]
	v_lshl_add_u64 v[180:181], s[90:91], 0, v[2:3]
	v_mov_b32_e32 v0, v1
	v_mov_b32_e32 v2, v1
	v_mov_b32_e32 v3, v1
	v_mov_b32_e32 v4, v1
	v_mov_b32_e32 v5, v1
	v_mov_b32_e32 v6, v1
	v_mov_b32_e32 v7, v1
	v_mov_b32_e32 v8, v1
	v_mov_b32_e32 v9, v1
	v_mov_b32_e32 v10, v1
	v_mov_b32_e32 v11, v1
	v_mov_b32_e32 v12, v1
	v_mov_b32_e32 v13, v1
	v_mov_b64_e32 v[30:31], v[14:15]
	v_mov_b64_e32 v[46:47], v[14:15]
	v_mov_b64_e32 v[62:63], v[14:15]
	v_mov_b64_e32 v[78:79], v[14:15]
	s_mov_b32 s86, 1
	s_mov_b32 s89, 0
	v_lshl_add_u32 v213, v210, 8, 0
	v_lshlrev_b32_e32 v230, 4, v211
	v_sub_u32_e32 v232, v210, v207
	v_mov_b32_e32 v234, 0xf149f2ca
	v_mov_b32_e32 v233, 0
	s_mov_b64 s[94:95], 0
	v_mov_b64_e32 v[28:29], v[12:13]
	v_mov_b64_e32 v[26:27], v[10:11]
	v_mov_b64_e32 v[24:25], v[8:9]
	v_mov_b64_e32 v[22:23], v[6:7]
	v_mov_b64_e32 v[20:21], v[4:5]
	v_mov_b64_e32 v[18:19], v[2:3]
	v_mov_b64_e32 v[16:17], v[0:1]
	v_mov_b64_e32 v[44:45], v[12:13]
	v_mov_b64_e32 v[42:43], v[10:11]
	v_mov_b64_e32 v[40:41], v[8:9]
	v_mov_b64_e32 v[38:39], v[6:7]
	v_mov_b64_e32 v[36:37], v[4:5]
	v_mov_b64_e32 v[34:35], v[2:3]
	v_mov_b64_e32 v[32:33], v[0:1]
	v_mov_b64_e32 v[60:61], v[12:13]
	v_mov_b64_e32 v[58:59], v[10:11]
	v_mov_b64_e32 v[56:57], v[8:9]
	v_mov_b64_e32 v[54:55], v[6:7]
	v_mov_b64_e32 v[52:53], v[4:5]
	v_mov_b64_e32 v[50:51], v[2:3]
	v_mov_b64_e32 v[48:49], v[0:1]
	v_mov_b64_e32 v[76:77], v[12:13]
	v_mov_b64_e32 v[74:75], v[10:11]
	v_mov_b64_e32 v[72:73], v[8:9]
	v_mov_b64_e32 v[70:71], v[6:7]
	v_mov_b64_e32 v[68:69], v[4:5]
	v_mov_b64_e32 v[66:67], v[2:3]
	v_mov_b64_e32 v[64:65], v[0:1]
	s_waitcnt vmcnt(0) lgkmcnt(0)
	s_barrier
	s_add_i32 s56, s86, -1
	s_and_b32 s56, s56, 1
	s_cmp_ge_u32 s86, s88
	s_cbranch_scc1 .LBB0_312

; __device__ __forceinline__ int v_rd_base(int lane) { return ((lane & 3) << 3) | (((lane >> 2) & 3) << 6) | (((lane >> 4) & 1) << 5) | (((lane >> 5) & 1) << 8); }
; #define FA_BAR() do { __builtin_amdgcn_s_barrier(); asm volatile("" ::: "memory"); } while (0)
; __device__ __forceinline__ void ret_block(const bf16_t* __restrict__ proj, const bf16_t* __restrict__ state, bf16_t* __restrict__ mixed, int b, int h, int qb, char* lds) {
;     int tid_ = threadIdx.x; asm volatile("" : "+v"(tid_));
;     const int tid = tid_, wid = __builtin_amdgcn_readfirstlane(tid >> 6), lane = tid & 63, r32 = lane & 31, hi = lane >> 5;
;     const int wq = wid & 3, e = wid >> 2;
;     constexpr int SHM = 32768;
;     char* V_lds = lds; char* K_lds = lds + 2 * SHM; float* ssx = (float*)(lds + 131072);
;     const bf16_t* Qp = proj + (size_t)(b * SEQ + qb * 128) * LDQ + 3072 + h * 256;
;     const bf16_t* Kp = proj + (size_t)(b * SEQ + qb * 128) * LDQ + 4096 + h * 256;
;     const bf16_t* Vp = Kp + 1024;
;     const bf16_t* Gp = Qp + 3072 + (size_t)(wq * 32) * LDQ + e * 128;
;     const bf16_t* Sp = state + (size_t)((b * 4 + h) * 16 + qb) * 65536;
;     bf16_t* Op = mixed + (size_t)(b * SEQ + qb * 128 + wq * 32) * LDO + 1024 + h * 256 + e * 128;
;     const int qlo = wq * 32, qm = qlo + r32 - 4 * hi;
;     bf16x8 qr[16];
; #pragma unroll
;     for (int d0 = 0; d0 < 16; ++d0) qr[d0] = *(const bf16x8*)(Qp + (size_t)(wq * 32 + r32) * LDQ + d0 * 16 + hi * 8);
;     const int lb = wid * 1024 + lane * 16;
;     const int krow = lb >> 9, kch = ((lb >> 4) & 31) ^ (krow & 7);
;     const bf16_t* kg = Kp + (size_t)krow * LDQ + kch * 8;
;     const int stv = lb >> 9, kkv = ((stv >> 3) << 3) | ((lb >> 6) & 7), kvv = (kkv & ~0xC) | ((kkv & 4) << 1) | ((kkv & 8) >> 1);
;     const bf16_t* vg = Vp + (size_t)kvv * LDQ + (stv & 7) * 32 + ((lb >> 4) & 3) * 8;
;     const bf16_t* sg = Sp + (size_t)kvv * 256 + (stv & 7) * 32 + ((lb >> 4) & 3) * 8;
;     ...
;     FA_DMA(0, 0); FA_DMA(64, 1);
;     f32x16 o[4];
; #pragma unroll
;     for (int d = 0; d < 4; ++d)
; #pragma unroll
;         for (int r = 0; r < 16; ++r) o[d][r] = 0.f;
;     const int vrd = v_rd_base(lane) + e * 2048;
;     const int vbV = (int)(uintptr_t)V_lds + vrd, vbK = (int)(uintptr_t)K_lds + vrd;
;     const bool has_state = qb > 0;
;     asm volatile("s_waitcnt vmcnt(8)" ::: "memory"); FA_BAR();
.LBB0_475:
	s_and_b64 s[0:1], s[34:35], exec
	s_cselect_b32 s69, s44, s43
	v_mov_b32_e32 v193, v185
	s_lshl_b32 s0, s69, 7
	s_or_b32 s50, s0, s45
	v_readfirstlane_b32 s52, v193
	s_ashr_i32 s4, s52, 6
	s_mul_i32 s1, s50, 0x3800
	s_mul_hi_i32 s0, s50, 0x3800
	s_add_u32 s1, s84, s1
	s_addc_u32 s0, s85, s0
	s_add_u32 s1, s1, s49
	s_addc_u32 s5, s0, 0
	s_add_u32 s36, s1, 0x1800
	s_addc_u32 s37, s5, 0
	s_add_u32 s0, s1, 0x2000
	s_addc_u32 s1, s5, 0
	s_lshl_b32 s5, s4, 5
	v_and_b32_e32 v194, 31, v193
	s_and_b32 s51, s5, 0x60
	v_or_b32_e32 v68, s51, v194
	v_mul_u32_u24_e32 v0, 0x1c00, v68
	v_bfe_u32 v192, v193, 5, 1
	v_lshlrev_b32_e32 v152, 1, v0
	v_lshl_add_u64 v[0:1], s[36:37], 0, v[152:153]
	v_lshlrev_b32_e32 v152, 4, v192
	v_lshl_add_u64 v[0:1], v[0:1], 0, v[152:153]
	global_load_dwordx4 v[140:143], v[0:1], off nt
	global_load_dwordx4 v[136:139], v[0:1], off offset:32 nt
	global_load_dwordx4 v[132:135], v[0:1], off offset:64 nt
	global_load_dwordx4 v[128:131], v[0:1], off offset:96 nt
	global_load_dwordx4 v[124:127], v[0:1], off offset:128 nt
	global_load_dwordx4 v[120:123], v[0:1], off offset:160 nt
	global_load_dwordx4 v[116:119], v[0:1], off offset:192 nt
	global_load_dwordx4 v[112:115], v[0:1], off offset:224 nt
	global_load_dwordx4 v[108:111], v[0:1], off offset:256 nt
	global_load_dwordx4 v[104:107], v[0:1], off offset:288 nt
	global_load_dwordx4 v[100:103], v[0:1], off offset:320 nt
	global_load_dwordx4 v[96:99], v[0:1], off offset:352 nt
	global_load_dwordx4 v[92:95], v[0:1], off offset:384 nt
	global_load_dwordx4 v[88:91], v[0:1], off offset:416 nt
	global_load_dwordx4 v[84:87], v[0:1], off offset:448 nt
	global_load_dwordx4 v[80:83], v[0:1], off offset:480 nt
	v_and_b32_e32 v20, 63, v193
	s_lshl_b32 s4, s4, 10
	v_lshlrev_b32_e32 v21, 4, v20
	v_or_b32_e32 v0, s4, v21
	v_ashrrev_i32_e32 v0, 9, v0
	v_and_b32_e32 v24, 7, v0
	v_bitop3_b32 v2, v0, v194, 7 bitop3:0x6c
	v_mul_hi_i32_i24_e32 v1, 0x3800, v0
	v_mul_i32_i24_e32 v0, 0x3800, v0
	v_lshl_add_u64 v[0:1], s[0:1], 0, v[0:1]
	v_lshlrev_b32_e32 v2, 4, v2
	v_mov_b32_e32 v3, v153
	v_lshl_add_u64 v[0:1], v[0:1], 0, v[2:3]
	s_ashr_i32 s5, s52, 5
	v_bfe_u32 v2, v193, 2, 2
	v_and_or_b32 v2, s5, -16, v2
	v_lshrrev_b32_e32 v3, 1, v193
	s_lshr_b32 s5, s5, 1
	v_and_b32_e32 v3, 8, v3
	s_and_b32 s5, s5, 4
	v_or3_b32 v16, v2, v3, s5
	v_mov_b64_e32 v[2:3], s[0:1]
	v_lshlrev_b32_e32 v23, 3, v20
	v_mad_i64_i32 v[2:3], s[0:1], v16, s33, v[2:3]
	v_lshlrev_b32_e32 v4, 6, v24
	v_mov_b32_e32 v5, v153
	v_and_b32_e32 v22, 24, v23
	v_lshl_add_u64 v[2:3], v[2:3], 0, v[4:5]
	v_lshlrev_b32_e32 v18, 1, v22
	v_mov_b32_e32 v19, v153
	s_add_i32 s5, s40, s4
	v_lshl_add_u64 v[2:3], v[2:3], 0, v[18:19]
	s_mov_b64 s[0:1], 0x800
	s_add_i32 s56, s4, 0
	s_mov_b32 m0, s5
	v_lshl_add_u64 v[4:5], v[2:3], 0, s[0:1]
	global_load_lds_dwordx4 v[0:1], off
	s_mov_b32 m0, s56
	s_mov_b64 s[0:1], 0x38000
	global_load_lds_dwordx4 v[4:5], off
	v_lshl_add_u64 v[4:5], v[0:1], 0, s[0:1]
	s_add_i32 m0, s5, 0x2000
	s_mov_b64 s[0:1], 0x38800
	s_add_i32 s57, s56, 0x2000
	global_load_lds_dwordx4 v[4:5], off
	v_lshl_add_u64 v[4:5], v[2:3], 0, s[0:1]
	s_mov_b32 m0, s57
	s_mov_b64 s[0:1], 0x70000
	global_load_lds_dwordx4 v[4:5], off
	v_lshl_add_u64 v[4:5], v[0:1], 0, s[0:1]
	s_add_i32 m0, s5, 0x4000
	s_mov_b64 s[0:1], 0x70800
	s_add_i32 s64, s56, 0x4000
	global_load_lds_dwordx4 v[4:5], off
	v_lshl_add_u64 v[4:5], v[2:3], 0, s[0:1]
	s_mov_b32 m0, s64
	s_mov_b64 s[0:1], 0xa8000
	global_load_lds_dwordx4 v[4:5], off
	v_lshl_add_u64 v[4:5], v[0:1], 0, s[0:1]
	s_add_i32 m0, s5, 0x6000
	s_mov_b64 s[0:1], 0xa8800
	s_add_i32 s65, s56, 0x6000
	global_load_lds_dwordx4 v[4:5], off
	v_lshl_add_u64 v[4:5], v[2:3], 0, s[0:1]
	s_mov_b32 m0, s65
	s_add_i32 s53, s56, 0x18000
	s_mov_b64 s[0:1], 0xe0000
	global_load_lds_dwordx4 v[4:5], off
	s_add_i32 s59, s56, 0x8000
	v_lshl_add_u64 v[4:5], v[0:1], 0, s[0:1]
	s_mov_b32 m0, s53
	s_mov_b64 s[0:1], 0xe0800
	global_load_lds_dwordx4 v[4:5], off
	v_lshl_add_u64 v[4:5], v[2:3], 0, s[0:1]
	s_mov_b32 m0, s59
	s_mov_b64 s[0:1], 0x118000
	s_add_i32 s54, s56, 0x1a000
	global_load_lds_dwordx4 v[4:5], off
	v_lshl_add_u64 v[4:5], v[0:1], 0, s[0:1]
	s_mov_b32 m0, s54
	s_mov_b64 s[0:1], 0x118800
	s_add_i32 s66, s56, 0xa000
	global_load_lds_dwordx4 v[4:5], off
	v_lshl_add_u64 v[4:5], v[2:3], 0, s[0:1]
	s_mov_b32 m0, s66
	s_mov_b64 s[0:1], 0x150000
	s_add_i32 s55, s56, 0x1c000
	global_load_lds_dwordx4 v[4:5], off
	v_lshl_add_u64 v[4:5], v[0:1], 0, s[0:1]
	s_mov_b32 m0, s55
	s_mov_b64 s[0:1], 0x150800
	s_add_i32 s67, s56, 0xc000
	global_load_lds_dwordx4 v[4:5], off
	v_lshl_add_u64 v[4:5], v[2:3], 0, s[0:1]
	s_mov_b32 m0, s67
	s_mov_b64 s[0:1], 0x188000
	s_add_i32 s58, s56, 0x1e000
	global_load_lds_dwordx4 v[4:5], off
	v_lshl_add_u64 v[0:1], v[0:1], 0, s[0:1]
	s_mov_b32 m0, s58
	s_mov_b64 s[0:1], 0x188800
	s_add_i32 s68, s56, 0xe000
	global_load_lds_dwordx4 v[0:1], off
	v_lshl_add_u64 v[0:1], v[2:3], 0, s[0:1]
	s_mov_b32 m0, s68
	v_lshlrev_b32_e32 v198, 9, v194
	v_lshlrev_b32_e32 v4, 4, v193
	s_movk_i32 s0, 0x70
	global_load_lds_dwordx4 v[0:1], off
	v_bitop3_b32 v196, v152, v4, s0 bitop3:0x78
	v_add_u32_e32 v17, s40, v198
	s_waitcnt vmcnt(8)
	s_barrier
; template <int NF, int RB>
; __device__ __forceinline__ void qkt1(f32x16& p, const char* Kt, int r32, int hi, const bf16x8* qr) {
; #pragma unroll
;     for (int r = 0; r < 16; ++r) p[r] = 0.f;
;     const char* kb[4];
; #pragma unroll
;     for (int dd = 0; dd < 4; ++dd) kb[dd] = Kt + r32 * RB + (((dd * 16 + hi * 8) * 2) ^ ((r32 & 7) << 4));
; #pragma unroll
;     for (int d0 = 0; d0 < NF; ++d0) { const bf16x8 b0 = *reinterpret_cast<const bf16x8*>(kb[d0 & 3] + (d0 >> 2) * 128);
;         p = __builtin_amdgcn_mfma_f32_32x32x16_bf16(b0, qr[d0], p, 0, 0, 0); }
; }
; __device__ __forceinline__ void ret_block(const bf16_t* __restrict__ proj, const bf16_t* __restrict__ state, bf16_t* __restrict__ mixed, int b, int h, int qb, char* lds) {
;     ...
;         if (kb <= qlo + 31) {
;             const bool diag = kb + 63 > qlo; const int dq = qm - kb;
;             bf16x8 pa0, pa1, pa2, pa3;
;             { f32x16 p; qkt1<16, 512>(p, K_lds + buf * SHM, r32, hi, qr);
;               if (diag) {
; #pragma unroll
;                   for (int r = 0; r < 16; ++r) { const int C = (r & 3) + 8 * (r >> 2); if (dq - C < 0) p[r] = 0.f; } }
	v_add_u32_e32 v19, v17, v196
	ds_read_b128 v[0:3], v19
	ds_read_b128 v[26:29], v19 offset:128
	v_and_b32_e32 v25, 0x70, v4
	v_bitop3_b32 v197, v152, v25, 32 bitop3:0x36
	v_add_u32_e32 v46, v17, v197
	ds_read_b128 v[30:33], v46
	ds_read_b128 v[34:37], v46 offset:128
	s_waitcnt vmcnt(0) lgkmcnt(0)
	v_mfma_f32_32x32x16_bf16 v[0:15], v[0:3], v[140:143], 0
	v_bitop3_b32 v199, v152, v25, 64 bitop3:0x36
	v_add_u32_e32 v47, v17, v199
	ds_read_b128 v[38:41], v47 offset:128
	s_movk_i32 s0, 0x60
	v_bitop3_b32 v200, v152, v25, s0 bitop3:0x36
	v_add_u32_e32 v17, v17, v200
	v_lshlrev_b32_e32 v191, 2, v192
	v_mfma_f32_32x32x16_bf16 v[0:15], v[30:33], v[136:139], v[0:15]
	ds_read_b128 v[30:33], v47
	s_cmp_lt_u32 s51, 63
	s_cselect_b64 s[38:39], -1, 0
	s_cmp_gt_u32 s51, 62
	s_waitcnt lgkmcnt(0)
	v_mfma_f32_32x32x16_bf16 v[0:15], v[30:33], v[132:135], v[0:15]
	ds_read_b128 v[30:33], v17
	ds_read_b128 v[42:45], v17 offset:128
	s_waitcnt lgkmcnt(1)
	v_mfma_f32_32x32x16_bf16 v[0:15], v[30:33], v[128:131], v[0:15]
	v_mfma_f32_32x32x16_bf16 v[0:15], v[26:29], v[124:127], v[0:15]
	ds_read_b128 v[26:29], v19 offset:256
	ds_read_b128 v[30:33], v19 offset:384
	v_mfma_f32_32x32x16_bf16 v[0:15], v[34:37], v[120:123], v[0:15]
	v_mfma_f32_32x32x16_bf16 v[0:15], v[38:41], v[116:119], v[0:15]
	s_waitcnt lgkmcnt(2)
	v_mfma_f32_32x32x16_bf16 v[0:15], v[42:45], v[112:115], v[0:15]
	s_waitcnt lgkmcnt(1)
	v_mfma_f32_32x32x16_bf16 v[0:15], v[26:29], v[108:111], v[0:15]
	ds_read_b128 v[26:29], v46 offset:256
	ds_read_b128 v[34:37], v46 offset:384
	s_waitcnt lgkmcnt(1)
	v_mfma_f32_32x32x16_bf16 v[0:15], v[26:29], v[104:107], v[0:15]
	ds_read_b128 v[26:29], v47 offset:256
	ds_read_b128 v[38:41], v47 offset:384
	s_waitcnt lgkmcnt(1)
	v_mfma_f32_32x32x16_bf16 v[0:15], v[26:29], v[100:103], v[0:15]
	ds_read_b128 v[26:29], v17 offset:256
	ds_read_b128 v[42:45], v17 offset:384
	v_sub_u32_e32 v17, v68, v191
	s_waitcnt lgkmcnt(1)
	v_mfma_f32_32x32x16_bf16 v[0:15], v[26:29], v[96:99], v[0:15]
	v_mfma_f32_32x32x16_bf16 v[0:15], v[30:33], v[92:95], v[0:15]
	v_mfma_f32_32x32x16_bf16 v[0:15], v[34:37], v[88:91], v[0:15]
	v_mfma_f32_32x32x16_bf16 v[0:15], v[38:41], v[84:87], v[0:15]
	s_waitcnt lgkmcnt(0)
	v_mfma_f32_32x32x16_bf16 v[0:15], v[42:45], v[80:83], v[0:15]
	s_cbranch_scc1 .LBB0_477
	v_cmp_gt_i32_e64 s[28:29], 26, v17
	v_cmp_gt_i32_e64 s[30:31], 27, v17
	v_cmp_gt_i32_e64 s[26:27], 25, v17
	s_and_b64 s[28:29], s[30:31], s[28:29]
	v_cmp_gt_i32_e64 s[24:25], 24, v17
	s_and_b64 s[26:27], s[28:29], s[26:27]
	v_cmp_gt_i32_e64 s[22:23], 19, v17
	s_and_b64 s[24:25], s[26:27], s[24:25]
	v_cmp_gt_i32_e64 s[20:21], 18, v17
	s_and_b64 s[22:23], s[24:25], s[22:23]
	v_cmp_gt_i32_e64 s[18:19], 17, v17
	s_and_b64 s[20:21], s[22:23], s[20:21]
	v_cmp_gt_i32_e64 s[16:17], 16, v17
	s_and_b64 s[18:19], s[20:21], s[18:19]
	v_cmp_gt_i32_e64 s[14:15], 11, v17
	s_and_b64 s[16:17], s[18:19], s[16:17]
	v_cmp_gt_i32_e64 s[12:13], 10, v17
	s_and_b64 s[14:15], s[16:17], s[14:15]
	v_cmp_gt_i32_e64 s[10:11], 9, v17
	s_and_b64 s[12:13], s[14:15], s[12:13]
	v_cmp_gt_i32_e64 s[8:9], 8, v17
	s_and_b64 s[10:11], s[12:13], s[10:11]
	v_cmp_gt_i32_e64 s[6:7], 3, v17
	s_and_b64 s[8:9], s[10:11], s[8:9]
	v_cmp_gt_i32_e64 s[4:5], 2, v17
	s_and_b64 s[6:7], s[8:9], s[6:7]
	v_cmp_gt_i32_e64 s[0:1], 1, v17
	s_and_b64 s[4:5], s[6:7], s[4:5]
	v_cmp_gt_i32_e32 vcc, 0, v17
	s_and_b64 s[0:1], s[4:5], s[0:1]
	v_cndmask_b32_e64 v1, v1, 0, s[0:1]
	s_and_b64 s[0:1], s[0:1], vcc
	v_cndmask_b32_e64 v15, v15, 0, s[30:31]
	v_cndmask_b32_e64 v14, v14, 0, s[28:29]
	v_cndmask_b32_e64 v13, v13, 0, s[26:27]
	v_cndmask_b32_e64 v12, v12, 0, s[24:25]
	v_cndmask_b32_e64 v11, v11, 0, s[22:23]
	v_cndmask_b32_e64 v10, v10, 0, s[20:21]
	v_cndmask_b32_e64 v9, v9, 0, s[18:19]
	v_cndmask_b32_e64 v8, v8, 0, s[16:17]
	v_cndmask_b32_e64 v7, v7, 0, s[14:15]
	v_cndmask_b32_e64 v6, v6, 0, s[12:13]
	v_cndmask_b32_e64 v5, v5, 0, s[10:11]
	v_cndmask_b32_e64 v4, v4, 0, s[8:9]
	v_cndmask_b32_e64 v3, v3, 0, s[6:7]
	v_cndmask_b32_e64 v2, v2, 0, s[4:5]
	v_cndmask_b32_e64 v0, v0, 0, s[0:1]
